# P6 epilogue: bias row + row sumsq parked in spare LDS by the K-loop's last iteration (LDS-DMA), epilogue reads them with ds_read instead of waiting on global loads
# speedup vs baseline: 1.0403x; 1.0012x over previous
.LBB0_846:
	s_add_u32 s30, s12, 0xfff80080
	s_addc_u32 s31, s13, -1
	s_cmp_eq_u32 s56, 28
	s_cselect_b32 s35, s25, s31
	s_cselect_b32 s34, s52, s30
	s_cselect_b32 s31, s23, s55
	s_cselect_b32 s30, s53, s54
	s_and_b64 vcc, exec, s[16:17]
	s_cbranch_vccz .Lk64_trail_p6
	s_sub_u32 vcc_lo, s54, 0x80
	s_subb_u32 vcc_hi, s55, 0
	s_add_i32 m0, s37, 0x18000
	s_nop 0
	global_load_lds_dwordx4 v148, vcc
	s_add_i32 m0, s37, 0x1a000
	s_nop 0
	global_load_lds_dwordx4 v144, vcc
	s_add_u32 vcc_lo, vcc_lo, 0x20000
	s_addc_u32 vcc_hi, vcc_hi, 0
	s_add_i32 m0, s37, 0x19000
	s_nop 0
	global_load_lds_dwordx4 v148, vcc
	s_add_i32 m0, s37, 0x1b000
	s_nop 0
	global_load_lds_dwordx4 v144, vcc
	s_add_u32 vcc_lo, vcc_lo, 0x60000
	s_addc_u32 vcc_hi, vcc_hi, 0
	s_add_i32 m0, s37, 0x1c000
	s_nop 0
	global_load_lds_dwordx4 v148, vcc
	s_add_i32 m0, s37, 0x1e000
	s_nop 0
	global_load_lds_dwordx4 v144, vcc
	s_add_u32 vcc_lo, vcc_lo, 0x20000
	s_addc_u32 vcc_hi, vcc_hi, 0
	s_add_i32 m0, s37, 0x1d000
	s_nop 0
	global_load_lds_dwordx4 v148, vcc
	s_add_i32 m0, s37, 0x1f000
	s_nop 0
	global_load_lds_dwordx4 v144, vcc
	s_cmp_eq_u32 s56, 28
	s_cbranch_scc0 .Lk64_epd_p6_l
	s_ashr_i32 vcc_lo, s10, 3
	s_mul_i32 vcc_lo, vcc_lo, 0xb000
	s_lshl_b32 vcc_hi, s11, 10
	s_add_i32 vcc_lo, vcc_lo, vcc_hi
	s_lshr_b32 vcc_hi, s37, 2
	s_add_i32 vcc_lo, vcc_lo, vcc_hi
	s_add_u32 vcc_lo, s66, vcc_lo
	s_addc_u32 vcc_hi, s67, 0
	v_and_b32_e32 v248, 63, v252
	v_lshlrev_b32_e32 v248, 2, v248
	s_lshr_b32 m0, s37, 2
	s_add_i32 m0, m0, 0x20000
	s_nop 0
	global_load_lds_dword v248, vcc
.Lk64_epd_p6_l:
	ds_read_b128 v[32:35], v169 offset:0
	ds_read_b128 v[36:39], v169 offset:1024
	ds_read_b128 v[40:43], v169 offset:2048
	ds_read_b128 v[44:47], v169 offset:3072
	ds_read_b128 v[162:165], v170 offset:0
	ds_read_b128 v[174:177], v170 offset:1024
	ds_read_b128 v[178:181], v170 offset:2048
	ds_read_b128 v[182:185], v170 offset:3072
	ds_read_b128 v[186:189], v171 offset:0
	ds_read_b128 v[190:193], v171 offset:1024
	ds_read_b128 v[194:197], v171 offset:2048
	ds_read_b128 v[198:201], v171 offset:3072
	ds_read_b128 v[202:205], v171 offset:4096
	ds_read_b128 v[206:209], v171 offset:5120
	ds_read_b128 v[210:213], v171 offset:6144
	ds_read_b128 v[214:217], v171 offset:7168
	ds_read_b128 v[220:223], v171 offset:16384
	ds_read_b128 v[224:227], v171 offset:17408
	ds_read_b128 v[228:231], v171 offset:18432
	ds_read_b128 v[232:235], v171 offset:19456
	ds_read_b128 v[236:239], v171 offset:20480
	ds_read_b128 v[240:243], v171 offset:21504
	ds_read_b128 v[244:247], v171 offset:22528
	ds_read_b128 v[248:251], v171 offset:23552
	s_nop 15
	s_nop 15
	s_waitcnt lgkmcnt(0)
	s_barrier
	s_setprio 1
	v_mfma_f32_16x16x32_bf16 v[140:143], v[32:35], v[186:189], v[140:143]
	v_mfma_f32_16x16x32_bf16 v[136:139], v[40:43], v[186:189], v[136:139]
	v_mfma_f32_16x16x32_bf16 v[124:127], v[32:35], v[194:197], v[124:127]
	v_mfma_f32_16x16x32_bf16 v[120:123], v[40:43], v[194:197], v[120:123]
	v_mfma_f32_16x16x32_bf16 v[108:111], v[32:35], v[202:205], v[108:111]
	v_mfma_f32_16x16x32_bf16 v[104:107], v[40:43], v[202:205], v[104:107]
	v_mfma_f32_16x16x32_bf16 v[92:95], v[32:35], v[210:213], v[92:95]
	v_mfma_f32_16x16x32_bf16 v[88:91], v[40:43], v[210:213], v[88:91]
	v_mfma_f32_16x16x32_bf16 v[140:143], v[36:39], v[190:193], v[140:143]
	v_mfma_f32_16x16x32_bf16 v[136:139], v[44:47], v[190:193], v[136:139]
	v_mfma_f32_16x16x32_bf16 v[124:127], v[36:39], v[198:201], v[124:127]
	v_mfma_f32_16x16x32_bf16 v[120:123], v[44:47], v[198:201], v[120:123]
	v_mfma_f32_16x16x32_bf16 v[108:111], v[36:39], v[206:209], v[108:111]
	v_mfma_f32_16x16x32_bf16 v[104:107], v[44:47], v[206:209], v[104:107]
	v_mfma_f32_16x16x32_bf16 v[92:95], v[36:39], v[214:217], v[92:95]
	v_mfma_f32_16x16x32_bf16 v[88:91], v[44:47], v[214:217], v[88:91]
	s_setprio 0
	s_setprio 1
	v_mfma_f32_16x16x32_bf16 v[132:135], v[162:165], v[186:189], v[132:135]
	v_mfma_f32_16x16x32_bf16 v[128:131], v[178:181], v[186:189], v[128:131]
	v_mfma_f32_16x16x32_bf16 v[116:119], v[162:165], v[194:197], v[116:119]
	v_mfma_f32_16x16x32_bf16 v[112:115], v[178:181], v[194:197], v[112:115]
	v_mfma_f32_16x16x32_bf16 v[100:103], v[162:165], v[202:205], v[100:103]
	v_mfma_f32_16x16x32_bf16 v[96:99], v[178:181], v[202:205], v[96:99]
	v_mfma_f32_16x16x32_bf16 v[84:87], v[162:165], v[210:213], v[84:87]
	v_mfma_f32_16x16x32_bf16 v[80:83], v[178:181], v[210:213], v[80:83]
	v_mfma_f32_16x16x32_bf16 v[132:135], v[174:177], v[190:193], v[132:135]
	v_mfma_f32_16x16x32_bf16 v[128:131], v[182:185], v[190:193], v[128:131]
	v_mfma_f32_16x16x32_bf16 v[116:119], v[174:177], v[198:201], v[116:119]
	v_mfma_f32_16x16x32_bf16 v[112:115], v[182:185], v[198:201], v[112:115]
	v_mfma_f32_16x16x32_bf16 v[100:103], v[174:177], v[206:209], v[100:103]
	v_mfma_f32_16x16x32_bf16 v[96:99], v[182:185], v[206:209], v[96:99]
	v_mfma_f32_16x16x32_bf16 v[84:87], v[174:177], v[214:217], v[84:87]
	v_mfma_f32_16x16x32_bf16 v[80:83], v[182:185], v[214:217], v[80:83]
	s_setprio 0
	s_setprio 1
	v_mfma_f32_16x16x32_bf16 v[76:79], v[32:35], v[220:223], v[76:79]
	v_mfma_f32_16x16x32_bf16 v[72:75], v[40:43], v[220:223], v[72:75]
	v_mfma_f32_16x16x32_bf16 v[60:63], v[32:35], v[228:231], v[60:63]
	v_mfma_f32_16x16x32_bf16 v[56:59], v[40:43], v[228:231], v[56:59]
	v_mfma_f32_16x16x32_bf16 v[28:31], v[32:35], v[236:239], v[28:31]
	v_mfma_f32_16x16x32_bf16 v[24:27], v[40:43], v[236:239], v[24:27]
	v_mfma_f32_16x16x32_bf16 v[12:15], v[32:35], v[244:247], v[12:15]
	v_mfma_f32_16x16x32_bf16 v[8:11], v[40:43], v[244:247], v[8:11]
	v_mfma_f32_16x16x32_bf16 v[76:79], v[36:39], v[224:227], v[76:79]
	v_mfma_f32_16x16x32_bf16 v[72:75], v[44:47], v[224:227], v[72:75]
	v_mfma_f32_16x16x32_bf16 v[60:63], v[36:39], v[232:235], v[60:63]
	v_mfma_f32_16x16x32_bf16 v[56:59], v[44:47], v[232:235], v[56:59]
	v_mfma_f32_16x16x32_bf16 v[28:31], v[36:39], v[240:243], v[28:31]
	v_mfma_f32_16x16x32_bf16 v[24:27], v[44:47], v[240:243], v[24:27]
	v_mfma_f32_16x16x32_bf16 v[12:15], v[36:39], v[248:251], v[12:15]
	v_mfma_f32_16x16x32_bf16 v[8:11], v[44:47], v[248:251], v[8:11]
	s_setprio 0
	s_setprio 1
	v_mfma_f32_16x16x32_bf16 v[68:71], v[162:165], v[220:223], v[68:71]
	v_mfma_f32_16x16x32_bf16 v[64:67], v[178:181], v[220:223], v[64:67]
	v_mfma_f32_16x16x32_bf16 v[52:55], v[162:165], v[228:231], v[52:55]
	v_mfma_f32_16x16x32_bf16 v[48:51], v[178:181], v[228:231], v[48:51]
	v_mfma_f32_16x16x32_bf16 v[20:23], v[162:165], v[236:239], v[20:23]
	v_mfma_f32_16x16x32_bf16 v[16:19], v[178:181], v[236:239], v[16:19]
	v_mfma_f32_16x16x32_bf16 v[4:7], v[162:165], v[244:247], v[4:7]
	v_mfma_f32_16x16x32_bf16 v[0:3], v[178:181], v[244:247], v[0:3]
	v_mfma_f32_16x16x32_bf16 v[68:71], v[174:177], v[224:227], v[68:71]
	v_mfma_f32_16x16x32_bf16 v[64:67], v[182:185], v[224:227], v[64:67]
	v_mfma_f32_16x16x32_bf16 v[52:55], v[174:177], v[232:235], v[52:55]
	v_mfma_f32_16x16x32_bf16 v[48:51], v[182:185], v[232:235], v[48:51]
	v_mfma_f32_16x16x32_bf16 v[20:23], v[174:177], v[240:243], v[20:23]
	v_mfma_f32_16x16x32_bf16 v[16:19], v[182:185], v[240:243], v[16:19]
	v_mfma_f32_16x16x32_bf16 v[4:7], v[174:177], v[248:251], v[4:7]
	v_mfma_f32_16x16x32_bf16 v[0:3], v[182:185], v[248:251], v[0:3]
	s_setprio 0
	s_waitcnt vmcnt(0)
	s_barrier
	s_add_u32 vcc_lo, s30, 0x0
	s_addc_u32 vcc_hi, s31, 0
	s_add_i32 m0, s37, 0x10000
	s_nop 0
	global_load_lds_dwordx4 v148, vcc
	s_add_i32 m0, s37, 0x12000
	s_nop 0
	global_load_lds_dwordx4 v144, vcc
	s_add_u32 vcc_lo, vcc_lo, 0x20000
	s_addc_u32 vcc_hi, vcc_hi, 0
	s_add_i32 m0, s37, 0x11000
	s_nop 0
	global_load_lds_dwordx4 v148, vcc
	s_add_i32 m0, s37, 0x13000
	s_nop 0
	global_load_lds_dwordx4 v144, vcc
	s_add_u32 vcc_lo, vcc_lo, 0x60000
	s_addc_u32 vcc_hi, vcc_hi, 0
	s_add_i32 m0, s37, 0x14000
	s_nop 0
	global_load_lds_dwordx4 v148, vcc
	s_add_i32 m0, s37, 0x16000
	s_nop 0
	global_load_lds_dwordx4 v144, vcc
	s_add_u32 vcc_lo, vcc_lo, 0x20000
	s_addc_u32 vcc_hi, vcc_hi, 0
	s_add_i32 m0, s37, 0x15000
	s_nop 0
	global_load_lds_dwordx4 v148, vcc
	s_add_i32 m0, s37, 0x17000
	s_nop 0
	global_load_lds_dwordx4 v144, vcc
	ds_read_b128 v[32:35], v169 offset:32768
	ds_read_b128 v[36:39], v169 offset:33792
	ds_read_b128 v[40:43], v169 offset:34816
	ds_read_b128 v[44:47], v169 offset:35840
	ds_read_b128 v[162:165], v170 offset:32768
	ds_read_b128 v[174:177], v170 offset:33792
	ds_read_b128 v[178:181], v170 offset:34816
	ds_read_b128 v[182:185], v170 offset:35840
	ds_read_b128 v[186:189], v171 offset:32768
	ds_read_b128 v[190:193], v171 offset:33792
	ds_read_b128 v[194:197], v171 offset:34816
	ds_read_b128 v[198:201], v171 offset:35840
	ds_read_b128 v[202:205], v171 offset:36864
	ds_read_b128 v[206:209], v171 offset:37888
	ds_read_b128 v[210:213], v171 offset:38912
	ds_read_b128 v[214:217], v171 offset:39936
	ds_read_b128 v[220:223], v171 offset:49152
	ds_read_b128 v[224:227], v171 offset:50176
	ds_read_b128 v[228:231], v171 offset:51200
	ds_read_b128 v[232:235], v171 offset:52224
	ds_read_b128 v[236:239], v171 offset:53248
	ds_read_b128 v[240:243], v171 offset:54272
	ds_read_b128 v[244:247], v171 offset:55296
	ds_read_b128 v[248:251], v171 offset:56320
	s_nop 15
	s_nop 15
	s_waitcnt lgkmcnt(0)
	s_barrier
	s_setprio 1
	v_mfma_f32_16x16x32_bf16 v[140:143], v[32:35], v[186:189], v[140:143]
	v_mfma_f32_16x16x32_bf16 v[136:139], v[40:43], v[186:189], v[136:139]
	v_mfma_f32_16x16x32_bf16 v[124:127], v[32:35], v[194:197], v[124:127]
	v_mfma_f32_16x16x32_bf16 v[120:123], v[40:43], v[194:197], v[120:123]
	v_mfma_f32_16x16x32_bf16 v[108:111], v[32:35], v[202:205], v[108:111]
	v_mfma_f32_16x16x32_bf16 v[104:107], v[40:43], v[202:205], v[104:107]
	v_mfma_f32_16x16x32_bf16 v[92:95], v[32:35], v[210:213], v[92:95]
	v_mfma_f32_16x16x32_bf16 v[88:91], v[40:43], v[210:213], v[88:91]
	v_mfma_f32_16x16x32_bf16 v[140:143], v[36:39], v[190:193], v[140:143]
	v_mfma_f32_16x16x32_bf16 v[136:139], v[44:47], v[190:193], v[136:139]
	v_mfma_f32_16x16x32_bf16 v[124:127], v[36:39], v[198:201], v[124:127]
	v_mfma_f32_16x16x32_bf16 v[120:123], v[44:47], v[198:201], v[120:123]
	v_mfma_f32_16x16x32_bf16 v[108:111], v[36:39], v[206:209], v[108:111]
	v_mfma_f32_16x16x32_bf16 v[104:107], v[44:47], v[206:209], v[104:107]
	v_mfma_f32_16x16x32_bf16 v[92:95], v[36:39], v[214:217], v[92:95]
	v_mfma_f32_16x16x32_bf16 v[88:91], v[44:47], v[214:217], v[88:91]
	s_setprio 0
	s_setprio 1
	v_mfma_f32_16x16x32_bf16 v[132:135], v[162:165], v[186:189], v[132:135]
	v_mfma_f32_16x16x32_bf16 v[128:131], v[178:181], v[186:189], v[128:131]
	v_mfma_f32_16x16x32_bf16 v[116:119], v[162:165], v[194:197], v[116:119]
	v_mfma_f32_16x16x32_bf16 v[112:115], v[178:181], v[194:197], v[112:115]
	v_mfma_f32_16x16x32_bf16 v[100:103], v[162:165], v[202:205], v[100:103]
	v_mfma_f32_16x16x32_bf16 v[96:99], v[178:181], v[202:205], v[96:99]
	v_mfma_f32_16x16x32_bf16 v[84:87], v[162:165], v[210:213], v[84:87]
	v_mfma_f32_16x16x32_bf16 v[80:83], v[178:181], v[210:213], v[80:83]
	v_mfma_f32_16x16x32_bf16 v[132:135], v[174:177], v[190:193], v[132:135]
	v_mfma_f32_16x16x32_bf16 v[128:131], v[182:185], v[190:193], v[128:131]
	v_mfma_f32_16x16x32_bf16 v[116:119], v[174:177], v[198:201], v[116:119]
	v_mfma_f32_16x16x32_bf16 v[112:115], v[182:185], v[198:201], v[112:115]
	v_mfma_f32_16x16x32_bf16 v[100:103], v[174:177], v[206:209], v[100:103]
	v_mfma_f32_16x16x32_bf16 v[96:99], v[182:185], v[206:209], v[96:99]
	v_mfma_f32_16x16x32_bf16 v[84:87], v[174:177], v[214:217], v[84:87]
	v_mfma_f32_16x16x32_bf16 v[80:83], v[182:185], v[214:217], v[80:83]
	s_setprio 0
	s_setprio 1
	v_mfma_f32_16x16x32_bf16 v[76:79], v[32:35], v[220:223], v[76:79]
	v_mfma_f32_16x16x32_bf16 v[72:75], v[40:43], v[220:223], v[72:75]
	v_mfma_f32_16x16x32_bf16 v[60:63], v[32:35], v[228:231], v[60:63]
	v_mfma_f32_16x16x32_bf16 v[56:59], v[40:43], v[228:231], v[56:59]
	v_mfma_f32_16x16x32_bf16 v[28:31], v[32:35], v[236:239], v[28:31]
	v_mfma_f32_16x16x32_bf16 v[24:27], v[40:43], v[236:239], v[24:27]
	v_mfma_f32_16x16x32_bf16 v[12:15], v[32:35], v[244:247], v[12:15]
	v_mfma_f32_16x16x32_bf16 v[8:11], v[40:43], v[244:247], v[8:11]
	v_mfma_f32_16x16x32_bf16 v[76:79], v[36:39], v[224:227], v[76:79]
	v_mfma_f32_16x16x32_bf16 v[72:75], v[44:47], v[224:227], v[72:75]
	v_mfma_f32_16x16x32_bf16 v[60:63], v[36:39], v[232:235], v[60:63]
	v_mfma_f32_16x16x32_bf16 v[56:59], v[44:47], v[232:235], v[56:59]
	v_mfma_f32_16x16x32_bf16 v[28:31], v[36:39], v[240:243], v[28:31]
	v_mfma_f32_16x16x32_bf16 v[24:27], v[44:47], v[240:243], v[24:27]
	v_mfma_f32_16x16x32_bf16 v[12:15], v[36:39], v[248:251], v[12:15]
	v_mfma_f32_16x16x32_bf16 v[8:11], v[44:47], v[248:251], v[8:11]
	s_setprio 0
	s_setprio 1
	v_mfma_f32_16x16x32_bf16 v[68:71], v[162:165], v[220:223], v[68:71]
	v_mfma_f32_16x16x32_bf16 v[64:67], v[178:181], v[220:223], v[64:67]
	v_mfma_f32_16x16x32_bf16 v[52:55], v[162:165], v[228:231], v[52:55]
	v_mfma_f32_16x16x32_bf16 v[48:51], v[178:181], v[228:231], v[48:51]
	v_mfma_f32_16x16x32_bf16 v[20:23], v[162:165], v[236:239], v[20:23]
	v_mfma_f32_16x16x32_bf16 v[16:19], v[178:181], v[236:239], v[16:19]
	v_mfma_f32_16x16x32_bf16 v[4:7], v[162:165], v[244:247], v[4:7]
	v_mfma_f32_16x16x32_bf16 v[0:3], v[178:181], v[244:247], v[0:3]
	v_mfma_f32_16x16x32_bf16 v[68:71], v[174:177], v[224:227], v[68:71]
	v_mfma_f32_16x16x32_bf16 v[64:67], v[182:185], v[224:227], v[64:67]
	v_mfma_f32_16x16x32_bf16 v[52:55], v[174:177], v[232:235], v[52:55]
	v_mfma_f32_16x16x32_bf16 v[48:51], v[182:185], v[232:235], v[48:51]
	v_mfma_f32_16x16x32_bf16 v[20:23], v[174:177], v[240:243], v[20:23]
	v_mfma_f32_16x16x32_bf16 v[16:19], v[182:185], v[240:243], v[16:19]
	v_mfma_f32_16x16x32_bf16 v[4:7], v[174:177], v[248:251], v[4:7]
	v_mfma_f32_16x16x32_bf16 v[0:3], v[182:185], v[248:251], v[0:3]
	s_setprio 0
	s_waitcnt vmcnt(0)
	s_barrier
	s_add_i32 s56, s56, 2
	s_add_u32 s12, s12, 0x100
	s_addc_u32 s13, s13, 0
	s_add_u32 s54, s54, 0x100
	s_addc_u32 s55, s55, 0
	s_cmp_gt_u32 s56, 29
	s_cbranch_scc0 .LBB0_846
	s_branch .Lk64_done_p6
.Lk64_trail_p6:
	s_sub_u32 vcc_lo, s12, 0x80000
	s_subb_u32 vcc_hi, s13, 0
	s_add_i32 m0, s37, 0xa000
	s_nop 0
	global_load_lds_dwordx4 v146, vcc
	s_add_u32 vcc_lo, vcc_lo, 0x20000
	s_addc_u32 vcc_hi, vcc_hi, 0
	s_add_i32 m0, s37, 0x9000
	s_nop 0
	global_load_lds_dwordx4 v150, vcc
	s_add_u32 vcc_lo, vcc_lo, 0x60000
	s_addc_u32 vcc_hi, vcc_hi, 0
	s_add_i32 m0, s37, 0xe000
	s_nop 0
	global_load_lds_dwordx4 v146, vcc
	s_add_u32 vcc_lo, vcc_lo, 0x20000
	s_addc_u32 vcc_hi, vcc_hi, 0
	s_add_i32 m0, s37, 0xd000
	s_nop 0
	global_load_lds_dwordx4 v150, vcc
	s_add_u32 vcc_lo, s34, 0x0
	s_addc_u32 vcc_hi, s35, 0
	s_mov_b32 m0, s37
	s_nop 0
	global_load_lds_dwordx4 v150, vcc
	s_sub_u32 vcc_lo, vcc_lo, 0x20000
	s_subb_u32 vcc_hi, vcc_hi, 0
	s_sub_i32 m0, s37, 0x1000
	s_nop 0
	global_load_lds_dwordx4 v150, vcc
	s_add_u32 vcc_lo, vcc_lo, 0xa0000
	s_addc_u32 vcc_hi, vcc_hi, 0
	s_add_i32 m0, s37, 0x4000
	s_nop 0
	global_load_lds_dwordx4 v150, vcc
	s_sub_u32 vcc_lo, vcc_lo, 0x20000
	s_subb_u32 vcc_hi, vcc_hi, 0
	s_add_i32 m0, s37, 0x3000
	s_nop 0
	global_load_lds_dwordx4 v150, vcc
	s_cmp_eq_u32 s56, 28
	s_cbranch_scc0 .Lk64_epd_p6_t
	s_lshl_b32 vcc_lo, s10, 10
	s_lshr_b32 vcc_hi, s37, 2
	s_add_i32 vcc_lo, vcc_lo, vcc_hi
	s_sub_i32 vcc_lo, vcc_lo, 0x400
	s_add_u32 vcc_lo, s18, vcc_lo
	s_addc_u32 vcc_hi, s19, 0
	v_and_b32_e32 v248, 63, v252
	v_lshlrev_b32_e32 v248, 2, v248
	s_lshr_b32 m0, s37, 2
	s_add_i32 m0, m0, 0x20000
	s_nop 0
	global_load_lds_dword v248, vcc
.Lk64_epd_p6_t:
	ds_read_b128 v[32:35], v169 offset:0
	ds_read_b128 v[36:39], v169 offset:1024
	ds_read_b128 v[40:43], v169 offset:2048
	ds_read_b128 v[44:47], v169 offset:3072
	ds_read_b128 v[162:165], v170 offset:0
	ds_read_b128 v[174:177], v170 offset:1024
	ds_read_b128 v[178:181], v170 offset:2048
	ds_read_b128 v[182:185], v170 offset:3072
	ds_read_b128 v[186:189], v171 offset:0
	ds_read_b128 v[190:193], v171 offset:1024
	ds_read_b128 v[194:197], v171 offset:2048
	ds_read_b128 v[198:201], v171 offset:3072
	ds_read_b128 v[202:205], v171 offset:4096
	ds_read_b128 v[206:209], v171 offset:5120
	ds_read_b128 v[210:213], v171 offset:6144
	ds_read_b128 v[214:217], v171 offset:7168
	ds_read_b128 v[220:223], v171 offset:16384
	ds_read_b128 v[224:227], v171 offset:17408
	ds_read_b128 v[228:231], v171 offset:18432
	ds_read_b128 v[232:235], v171 offset:19456
	ds_read_b128 v[236:239], v171 offset:20480
	ds_read_b128 v[240:243], v171 offset:21504
	ds_read_b128 v[244:247], v171 offset:22528
	ds_read_b128 v[248:251], v171 offset:23552
	s_nop 15
	s_nop 15
	s_waitcnt lgkmcnt(0)
	s_barrier
	s_setprio 1
	v_mfma_f32_16x16x32_bf16 v[140:143], v[32:35], v[186:189], v[140:143]
	v_mfma_f32_16x16x32_bf16 v[136:139], v[40:43], v[186:189], v[136:139]
	v_mfma_f32_16x16x32_bf16 v[124:127], v[32:35], v[194:197], v[124:127]
	v_mfma_f32_16x16x32_bf16 v[120:123], v[40:43], v[194:197], v[120:123]
	v_mfma_f32_16x16x32_bf16 v[108:111], v[32:35], v[202:205], v[108:111]
	v_mfma_f32_16x16x32_bf16 v[104:107], v[40:43], v[202:205], v[104:107]
	v_mfma_f32_16x16x32_bf16 v[92:95], v[32:35], v[210:213], v[92:95]
	v_mfma_f32_16x16x32_bf16 v[88:91], v[40:43], v[210:213], v[88:91]
	v_mfma_f32_16x16x32_bf16 v[140:143], v[36:39], v[190:193], v[140:143]
	v_mfma_f32_16x16x32_bf16 v[136:139], v[44:47], v[190:193], v[136:139]
	v_mfma_f32_16x16x32_bf16 v[124:127], v[36:39], v[198:201], v[124:127]
	v_mfma_f32_16x16x32_bf16 v[120:123], v[44:47], v[198:201], v[120:123]
	v_mfma_f32_16x16x32_bf16 v[108:111], v[36:39], v[206:209], v[108:111]
	v_mfma_f32_16x16x32_bf16 v[104:107], v[44:47], v[206:209], v[104:107]
	v_mfma_f32_16x16x32_bf16 v[92:95], v[36:39], v[214:217], v[92:95]
	v_mfma_f32_16x16x32_bf16 v[88:91], v[44:47], v[214:217], v[88:91]
	s_setprio 0
	s_setprio 1
	v_mfma_f32_16x16x32_bf16 v[132:135], v[162:165], v[186:189], v[132:135]
	v_mfma_f32_16x16x32_bf16 v[128:131], v[178:181], v[186:189], v[128:131]
	v_mfma_f32_16x16x32_bf16 v[116:119], v[162:165], v[194:197], v[116:119]
	v_mfma_f32_16x16x32_bf16 v[112:115], v[178:181], v[194:197], v[112:115]
	v_mfma_f32_16x16x32_bf16 v[100:103], v[162:165], v[202:205], v[100:103]
	v_mfma_f32_16x16x32_bf16 v[96:99], v[178:181], v[202:205], v[96:99]
	v_mfma_f32_16x16x32_bf16 v[84:87], v[162:165], v[210:213], v[84:87]
	v_mfma_f32_16x16x32_bf16 v[80:83], v[178:181], v[210:213], v[80:83]
	v_mfma_f32_16x16x32_bf16 v[132:135], v[174:177], v[190:193], v[132:135]
	v_mfma_f32_16x16x32_bf16 v[128:131], v[182:185], v[190:193], v[128:131]
	v_mfma_f32_16x16x32_bf16 v[116:119], v[174:177], v[198:201], v[116:119]
	v_mfma_f32_16x16x32_bf16 v[112:115], v[182:185], v[198:201], v[112:115]
	v_mfma_f32_16x16x32_bf16 v[100:103], v[174:177], v[206:209], v[100:103]
	v_mfma_f32_16x16x32_bf16 v[96:99], v[182:185], v[206:209], v[96:99]
	v_mfma_f32_16x16x32_bf16 v[84:87], v[174:177], v[214:217], v[84:87]
	v_mfma_f32_16x16x32_bf16 v[80:83], v[182:185], v[214:217], v[80:83]
	s_setprio 0
	s_setprio 1
	v_mfma_f32_16x16x32_bf16 v[76:79], v[32:35], v[220:223], v[76:79]
	v_mfma_f32_16x16x32_bf16 v[72:75], v[40:43], v[220:223], v[72:75]
	v_mfma_f32_16x16x32_bf16 v[60:63], v[32:35], v[228:231], v[60:63]
	v_mfma_f32_16x16x32_bf16 v[56:59], v[40:43], v[228:231], v[56:59]
	v_mfma_f32_16x16x32_bf16 v[28:31], v[32:35], v[236:239], v[28:31]
	v_mfma_f32_16x16x32_bf16 v[24:27], v[40:43], v[236:239], v[24:27]
	v_mfma_f32_16x16x32_bf16 v[12:15], v[32:35], v[244:247], v[12:15]
	v_mfma_f32_16x16x32_bf16 v[8:11], v[40:43], v[244:247], v[8:11]
	v_mfma_f32_16x16x32_bf16 v[76:79], v[36:39], v[224:227], v[76:79]
	v_mfma_f32_16x16x32_bf16 v[72:75], v[44:47], v[224:227], v[72:75]
	v_mfma_f32_16x16x32_bf16 v[60:63], v[36:39], v[232:235], v[60:63]
	v_mfma_f32_16x16x32_bf16 v[56:59], v[44:47], v[232:235], v[56:59]
	v_mfma_f32_16x16x32_bf16 v[28:31], v[36:39], v[240:243], v[28:31]
	v_mfma_f32_16x16x32_bf16 v[24:27], v[44:47], v[240:243], v[24:27]
	v_mfma_f32_16x16x32_bf16 v[12:15], v[36:39], v[248:251], v[12:15]
	v_mfma_f32_16x16x32_bf16 v[8:11], v[44:47], v[248:251], v[8:11]
	s_setprio 0
	s_setprio 1
	v_mfma_f32_16x16x32_bf16 v[68:71], v[162:165], v[220:223], v[68:71]
	v_mfma_f32_16x16x32_bf16 v[64:67], v[178:181], v[220:223], v[64:67]
	v_mfma_f32_16x16x32_bf16 v[52:55], v[162:165], v[228:231], v[52:55]
	v_mfma_f32_16x16x32_bf16 v[48:51], v[178:181], v[228:231], v[48:51]
	v_mfma_f32_16x16x32_bf16 v[20:23], v[162:165], v[236:239], v[20:23]
	v_mfma_f32_16x16x32_bf16 v[16:19], v[178:181], v[236:239], v[16:19]
	v_mfma_f32_16x16x32_bf16 v[4:7], v[162:165], v[244:247], v[4:7]
	v_mfma_f32_16x16x32_bf16 v[0:3], v[178:181], v[244:247], v[0:3]
	v_mfma_f32_16x16x32_bf16 v[68:71], v[174:177], v[224:227], v[68:71]
	v_mfma_f32_16x16x32_bf16 v[64:67], v[182:185], v[224:227], v[64:67]
	v_mfma_f32_16x16x32_bf16 v[52:55], v[174:177], v[232:235], v[52:55]
	v_mfma_f32_16x16x32_bf16 v[48:51], v[182:185], v[232:235], v[48:51]
	v_mfma_f32_16x16x32_bf16 v[20:23], v[174:177], v[240:243], v[20:23]
	v_mfma_f32_16x16x32_bf16 v[16:19], v[182:185], v[240:243], v[16:19]
	v_mfma_f32_16x16x32_bf16 v[4:7], v[174:177], v[248:251], v[4:7]
	v_mfma_f32_16x16x32_bf16 v[0:3], v[182:185], v[248:251], v[0:3]
	s_setprio 0
	s_waitcnt vmcnt(0)
	s_barrier
	s_add_u32 vcc_lo, s34, 0x0
	s_addc_u32 vcc_hi, s35, 0
	s_add_i32 m0, s37, 0x2000
	s_nop 0
	global_load_lds_dwordx4 v146, vcc
	s_add_u32 vcc_lo, vcc_lo, 0x20000
	s_addc_u32 vcc_hi, vcc_hi, 0
	s_add_i32 m0, s37, 0x1000
	s_nop 0
	global_load_lds_dwordx4 v150, vcc
	s_add_u32 vcc_lo, vcc_lo, 0x60000
	s_addc_u32 vcc_hi, vcc_hi, 0
	s_add_i32 m0, s37, 0x6000
	s_nop 0
	global_load_lds_dwordx4 v146, vcc
	s_add_u32 vcc_lo, vcc_lo, 0x20000
	s_addc_u32 vcc_hi, vcc_hi, 0
	s_add_i32 m0, s37, 0x5000
	s_nop 0
	global_load_lds_dwordx4 v150, vcc
	s_add_u32 vcc_lo, s34, 0x80
	s_addc_u32 vcc_hi, s35, 0
	s_add_i32 m0, s37, 0x8000
	s_nop 0
	global_load_lds_dwordx4 v150, vcc
	s_sub_u32 vcc_lo, vcc_lo, 0x20000
	s_subb_u32 vcc_hi, vcc_hi, 0
	s_add_i32 m0, s37, 0x7000
	s_nop 0
	global_load_lds_dwordx4 v150, vcc
	s_add_u32 vcc_lo, vcc_lo, 0xa0000
	s_addc_u32 vcc_hi, vcc_hi, 0
	s_add_i32 m0, s37, 0xc000
	s_nop 0
	global_load_lds_dwordx4 v150, vcc
	s_sub_u32 vcc_lo, vcc_lo, 0x20000
	s_subb_u32 vcc_hi, vcc_hi, 0
	s_add_i32 m0, s37, 0xb000
	s_nop 0
	global_load_lds_dwordx4 v150, vcc
	ds_read_b128 v[32:35], v169 offset:32768
	ds_read_b128 v[36:39], v169 offset:33792
	ds_read_b128 v[40:43], v169 offset:34816
	ds_read_b128 v[44:47], v169 offset:35840
	ds_read_b128 v[162:165], v170 offset:32768
	ds_read_b128 v[174:177], v170 offset:33792
	ds_read_b128 v[178:181], v170 offset:34816
	ds_read_b128 v[182:185], v170 offset:35840
	ds_read_b128 v[186:189], v171 offset:32768
	ds_read_b128 v[190:193], v171 offset:33792
	ds_read_b128 v[194:197], v171 offset:34816
	ds_read_b128 v[198:201], v171 offset:35840
	ds_read_b128 v[202:205], v171 offset:36864
	ds_read_b128 v[206:209], v171 offset:37888
	ds_read_b128 v[210:213], v171 offset:38912
	ds_read_b128 v[214:217], v171 offset:39936
	ds_read_b128 v[220:223], v171 offset:49152
	ds_read_b128 v[224:227], v171 offset:50176
	ds_read_b128 v[228:231], v171 offset:51200
	ds_read_b128 v[232:235], v171 offset:52224
	ds_read_b128 v[236:239], v171 offset:53248
	ds_read_b128 v[240:243], v171 offset:54272
	ds_read_b128 v[244:247], v171 offset:55296
	ds_read_b128 v[248:251], v171 offset:56320
	s_nop 15
	s_nop 15
	s_waitcnt lgkmcnt(0)
	s_barrier
	s_setprio 1
	v_mfma_f32_16x16x32_bf16 v[140:143], v[32:35], v[186:189], v[140:143]
	v_mfma_f32_16x16x32_bf16 v[136:139], v[40:43], v[186:189], v[136:139]
	v_mfma_f32_16x16x32_bf16 v[124:127], v[32:35], v[194:197], v[124:127]
	v_mfma_f32_16x16x32_bf16 v[120:123], v[40:43], v[194:197], v[120:123]
	v_mfma_f32_16x16x32_bf16 v[108:111], v[32:35], v[202:205], v[108:111]
	v_mfma_f32_16x16x32_bf16 v[104:107], v[40:43], v[202:205], v[104:107]
	v_mfma_f32_16x16x32_bf16 v[92:95], v[32:35], v[210:213], v[92:95]
	v_mfma_f32_16x16x32_bf16 v[88:91], v[40:43], v[210:213], v[88:91]
	v_mfma_f32_16x16x32_bf16 v[140:143], v[36:39], v[190:193], v[140:143]
	v_mfma_f32_16x16x32_bf16 v[136:139], v[44:47], v[190:193], v[136:139]
	v_mfma_f32_16x16x32_bf16 v[124:127], v[36:39], v[198:201], v[124:127]
	v_mfma_f32_16x16x32_bf16 v[120:123], v[44:47], v[198:201], v[120:123]
	v_mfma_f32_16x16x32_bf16 v[108:111], v[36:39], v[206:209], v[108:111]
	v_mfma_f32_16x16x32_bf16 v[104:107], v[44:47], v[206:209], v[104:107]
	v_mfma_f32_16x16x32_bf16 v[92:95], v[36:39], v[214:217], v[92:95]
	v_mfma_f32_16x16x32_bf16 v[88:91], v[44:47], v[214:217], v[88:91]
	s_setprio 0
	s_setprio 1
	v_mfma_f32_16x16x32_bf16 v[132:135], v[162:165], v[186:189], v[132:135]
	v_mfma_f32_16x16x32_bf16 v[128:131], v[178:181], v[186:189], v[128:131]
	v_mfma_f32_16x16x32_bf16 v[116:119], v[162:165], v[194:197], v[116:119]
	v_mfma_f32_16x16x32_bf16 v[112:115], v[178:181], v[194:197], v[112:115]
	v_mfma_f32_16x16x32_bf16 v[100:103], v[162:165], v[202:205], v[100:103]
	v_mfma_f32_16x16x32_bf16 v[96:99], v[178:181], v[202:205], v[96:99]
	v_mfma_f32_16x16x32_bf16 v[84:87], v[162:165], v[210:213], v[84:87]
	v_mfma_f32_16x16x32_bf16 v[80:83], v[178:181], v[210:213], v[80:83]
	v_mfma_f32_16x16x32_bf16 v[132:135], v[174:177], v[190:193], v[132:135]
	v_mfma_f32_16x16x32_bf16 v[128:131], v[182:185], v[190:193], v[128:131]
	v_mfma_f32_16x16x32_bf16 v[116:119], v[174:177], v[198:201], v[116:119]
	v_mfma_f32_16x16x32_bf16 v[112:115], v[182:185], v[198:201], v[112:115]
	v_mfma_f32_16x16x32_bf16 v[100:103], v[174:177], v[206:209], v[100:103]
	v_mfma_f32_16x16x32_bf16 v[96:99], v[182:185], v[206:209], v[96:99]
	v_mfma_f32_16x16x32_bf16 v[84:87], v[174:177], v[214:217], v[84:87]
	v_mfma_f32_16x16x32_bf16 v[80:83], v[182:185], v[214:217], v[80:83]
	s_setprio 0
	s_setprio 1
	v_mfma_f32_16x16x32_bf16 v[76:79], v[32:35], v[220:223], v[76:79]
	v_mfma_f32_16x16x32_bf16 v[72:75], v[40:43], v[220:223], v[72:75]
	v_mfma_f32_16x16x32_bf16 v[60:63], v[32:35], v[228:231], v[60:63]
	v_mfma_f32_16x16x32_bf16 v[56:59], v[40:43], v[228:231], v[56:59]
	v_mfma_f32_16x16x32_bf16 v[28:31], v[32:35], v[236:239], v[28:31]
	v_mfma_f32_16x16x32_bf16 v[24:27], v[40:43], v[236:239], v[24:27]
	v_mfma_f32_16x16x32_bf16 v[12:15], v[32:35], v[244:247], v[12:15]
	v_mfma_f32_16x16x32_bf16 v[8:11], v[40:43], v[244:247], v[8:11]
	v_mfma_f32_16x16x32_bf16 v[76:79], v[36:39], v[224:227], v[76:79]
	v_mfma_f32_16x16x32_bf16 v[72:75], v[44:47], v[224:227], v[72:75]
	v_mfma_f32_16x16x32_bf16 v[60:63], v[36:39], v[232:235], v[60:63]
	v_mfma_f32_16x16x32_bf16 v[56:59], v[44:47], v[232:235], v[56:59]
	v_mfma_f32_16x16x32_bf16 v[28:31], v[36:39], v[240:243], v[28:31]
	v_mfma_f32_16x16x32_bf16 v[24:27], v[44:47], v[240:243], v[24:27]
	v_mfma_f32_16x16x32_bf16 v[12:15], v[36:39], v[248:251], v[12:15]
	v_mfma_f32_16x16x32_bf16 v[8:11], v[44:47], v[248:251], v[8:11]
	s_setprio 0
	s_setprio 1
	v_mfma_f32_16x16x32_bf16 v[68:71], v[162:165], v[220:223], v[68:71]
	v_mfma_f32_16x16x32_bf16 v[64:67], v[178:181], v[220:223], v[64:67]
	v_mfma_f32_16x16x32_bf16 v[52:55], v[162:165], v[228:231], v[52:55]
	v_mfma_f32_16x16x32_bf16 v[48:51], v[178:181], v[228:231], v[48:51]
	v_mfma_f32_16x16x32_bf16 v[20:23], v[162:165], v[236:239], v[20:23]
	v_mfma_f32_16x16x32_bf16 v[16:19], v[178:181], v[236:239], v[16:19]
	v_mfma_f32_16x16x32_bf16 v[4:7], v[162:165], v[244:247], v[4:7]
	v_mfma_f32_16x16x32_bf16 v[0:3], v[178:181], v[244:247], v[0:3]
	v_mfma_f32_16x16x32_bf16 v[68:71], v[174:177], v[224:227], v[68:71]
	v_mfma_f32_16x16x32_bf16 v[64:67], v[182:185], v[224:227], v[64:67]
	v_mfma_f32_16x16x32_bf16 v[52:55], v[174:177], v[232:235], v[52:55]
	v_mfma_f32_16x16x32_bf16 v[48:51], v[182:185], v[232:235], v[48:51]
	v_mfma_f32_16x16x32_bf16 v[20:23], v[174:177], v[240:243], v[20:23]
	v_mfma_f32_16x16x32_bf16 v[16:19], v[182:185], v[240:243], v[16:19]
	v_mfma_f32_16x16x32_bf16 v[4:7], v[174:177], v[248:251], v[4:7]
	v_mfma_f32_16x16x32_bf16 v[0:3], v[182:185], v[248:251], v[0:3]
	s_setprio 0
	s_waitcnt vmcnt(0)
	s_barrier
	s_add_i32 s56, s56, 2
	s_add_u32 s12, s12, 0x100
	s_addc_u32 s13, s13, 0
	s_add_u32 s54, s54, 0x100
	s_addc_u32 s55, s55, 0
	s_cmp_gt_u32 s56, 29
	s_cbranch_scc0 .LBB0_846

.LBB0_849:
	v_lshl_add_u32 v162, s10, 8, v166
	s_ashr_i32 s10, s10, 3
	s_mul_hi_i32 s13, s10, 0xb000
	s_mul_i32 s10, s10, 0xb000
	v_lshl_or_b32 v32, s11, 8, v168
	s_add_u32 s12, s66, s10
	s_addc_u32 s13, s67, s13
	v_ashrrev_i32_e32 v33, 31, v32
	v_ashrrev_i32_e32 v163, 31, v162
	v_lshlrev_b32_e32 v40, 2, v168
	v_lshlrev_b32_e32 v164, 2, v166
	v_add_u32_e32 v40, 0x20000, v40
	v_add_u32_e32 v164, 0x20400, v164
	ds_read_b128 v[36:39], v40 offset:16
	ds_read_b128 v[44:47], v40
	ds_read_b128 v[32:35], v40 offset:528
	s_lshl_b32 s10, s11, 7
	ds_read_b32 v163, v164
	ds_read_b32 v178, v164 offset:64
	ds_read_b32 v179, v164 offset:128
	ds_read_b32 v180, v164 offset:192
	ds_read_b32 v181, v164 offset:512
	ds_read_b32 v182, v164 offset:576
	ds_read_b32 v183, v164 offset:640
	ds_read_b32 v184, v164 offset:704
	s_ashr_i32 s11, s10, 31
	s_lshl_b64 s[10:11], s[10:11], 1
	s_andn2_b64 vcc, exec, s[40:41]
	ds_read_b128 v[40:43], v40 offset:512
	s_waitcnt lgkmcnt(0)
	v_fmamk_f32 v163, v163, 0x3a000000, v172
	v_rsq_f32_e32 v174, v163
	s_nop 0
	v_pk_fma_f32 v[140:141], v[140:141], v[174:175], v[44:45] op_sel_hi:[1,0,1]
	s_nop 0
	v_mul_f32_e32 v163, 0xbfb8aa3b, v140
	v_exp_f32_e32 v163, v163
	v_pk_fma_f32 v[142:143], v[142:143], v[174:175], v[46:47] op_sel_hi:[1,0,1]
	v_pk_fma_f32 v[138:139], v[138:139], v[174:175], v[38:39] op_sel_hi:[1,0,1]
	v_pk_fma_f32 v[136:137], v[136:137], v[174:175], v[36:37] op_sel_hi:[1,0,1]
	v_add_f32_e32 v163, 1.0, v163
	v_pk_fma_f32 v[132:133], v[132:133], v[174:175], v[40:41] op_sel_hi:[1,0,1]
	v_pk_fma_f32 v[134:135], v[134:135], v[174:175], v[42:43] op_sel_hi:[1,0,1]
	v_pk_fma_f32 v[128:129], v[128:129], v[174:175], v[32:33] op_sel_hi:[1,0,1]
	v_pk_fma_f32 v[130:131], v[130:131], v[174:175], v[34:35] op_sel_hi:[1,0,1]
	v_rcp_f32_e32 v174, v163
	v_mul_f32_e32 v163, 0xbfb8aa3b, v141
	v_exp_f32_e32 v163, v163
	s_nop 0
	v_add_f32_e32 v163, 1.0, v163
	v_rcp_f32_e32 v175, v163
	v_mul_f32_e32 v163, 0xbfb8aa3b, v142
	v_exp_f32_e32 v163, v163
	v_pk_mul_f32 v[140:141], v[140:141], v[174:175]
	s_nop 0
	v_pk_mul_f32 v[132:133], v[132:133], v[140:141]
	v_add_f32_e32 v163, 1.0, v163
	v_rcp_f32_e32 v176, v163
	v_mul_f32_e32 v163, 0xbfb8aa3b, v143
	v_exp_f32_e32 v163, v163
	v_mul_f32_e32 v140, 0xbfb8aa3b, v136
	v_mul_f32_e32 v141, 0xbfb8aa3b, v137
	v_exp_f32_e32 v140, v140
	v_add_f32_e32 v163, 1.0, v163
	v_rcp_f32_e32 v177, v163
	v_exp_f32_e32 v141, v141
	v_add_f32_e32 v140, 1.0, v140
	v_rcp_f32_e32 v140, v140
	v_pk_mul_f32 v[142:143], v[142:143], v[176:177]
	v_add_f32_e32 v141, 1.0, v141
	v_pk_mul_f32 v[134:135], v[134:135], v[142:143]
	v_mul_f32_e32 v142, 0xbfb8aa3b, v138
	v_mul_f32_e32 v143, 0xbfb8aa3b, v139
	v_exp_f32_e32 v142, v142
	v_exp_f32_e32 v143, v143
	v_rcp_f32_e32 v141, v141
	v_add_f32_e32 v142, 1.0, v142
	v_add_f32_e32 v143, 1.0, v143
	v_rcp_f32_e32 v142, v142
	v_rcp_f32_e32 v143, v143
	v_pk_mul_f32 v[136:137], v[136:137], v[140:141]
	v_pk_mul_f32 v[138:139], v[138:139], v[142:143]
	v_pk_mul_f32 v[128:129], v[128:129], v[136:137]
	v_pk_mul_f32 v[138:139], v[130:131], v[138:139]
	v_cvt_pk_bf16_f32 v130, v132, v133
	v_cvt_pk_bf16_f32 v132, v128, v129
	v_mov_b64_e32 v[128:129], s[8:9]
	v_cvt_pk_bf16_f32 v131, v134, v135
	v_mad_i64_i32 v[134:135], s[12:13], v162, s49, v[128:129]
	v_lshl_add_u64 v[134:135], v[134:135], 0, s[10:11]
	v_lshl_add_u64 v[134:135], v[134:135], 0, s[0:1]
	v_cvt_pk_bf16_f32 v133, v138, v139
	v_lshl_add_u64 v[134:135], v[134:135], 0, v[152:153]
	global_store_dwordx4 v[134:135], v[130:133], off
	s_nop 1
	v_or_b32_e32 v130, 16, v162
	v_ashrrev_i32_e32 v131, 31, v130
	v_lshl_add_u64 v[132:133], v[130:131], 2, s[18:19]
	s_nop 1
	v_fmamk_f32 v131, v178, 0x3a000000, v172
	v_rsq_f32_e32 v132, v131
	s_nop 0
	v_pk_fma_f32 v[124:125], v[124:125], v[132:133], v[44:45] op_sel_hi:[1,0,1]
	s_nop 0
	v_mul_f32_e32 v131, 0xbfb8aa3b, v124
	v_exp_f32_e32 v131, v131
	v_pk_fma_f32 v[126:127], v[126:127], v[132:133], v[46:47] op_sel_hi:[1,0,1]
	v_pk_fma_f32 v[122:123], v[122:123], v[132:133], v[38:39] op_sel_hi:[1,0,1]
	v_pk_fma_f32 v[120:121], v[120:121], v[132:133], v[36:37] op_sel_hi:[1,0,1]
	v_add_f32_e32 v131, 1.0, v131
	v_pk_fma_f32 v[116:117], v[116:117], v[132:133], v[40:41] op_sel_hi:[1,0,1]
	v_pk_fma_f32 v[118:119], v[118:119], v[132:133], v[42:43] op_sel_hi:[1,0,1]
	v_pk_fma_f32 v[112:113], v[112:113], v[132:133], v[32:33] op_sel_hi:[1,0,1]
	v_pk_fma_f32 v[114:115], v[114:115], v[132:133], v[34:35] op_sel_hi:[1,0,1]
	v_rcp_f32_e32 v132, v131
	v_mul_f32_e32 v131, 0xbfb8aa3b, v125
	v_exp_f32_e32 v131, v131
	s_nop 0
	v_add_f32_e32 v131, 1.0, v131
	v_rcp_f32_e32 v133, v131
	v_mul_f32_e32 v131, 0xbfb8aa3b, v126
	v_exp_f32_e32 v131, v131
	v_pk_mul_f32 v[124:125], v[124:125], v[132:133]
	s_nop 0
	v_pk_mul_f32 v[116:117], v[116:117], v[124:125]
	v_add_f32_e32 v131, 1.0, v131
	v_rcp_f32_e32 v134, v131
	v_mul_f32_e32 v131, 0xbfb8aa3b, v127
	v_exp_f32_e32 v131, v131
	v_mul_f32_e32 v124, 0xbfb8aa3b, v120
	v_mul_f32_e32 v125, 0xbfb8aa3b, v121
	v_exp_f32_e32 v124, v124
	v_add_f32_e32 v131, 1.0, v131
	v_rcp_f32_e32 v135, v131
	v_exp_f32_e32 v125, v125
	v_add_f32_e32 v124, 1.0, v124
	v_rcp_f32_e32 v124, v124
	v_pk_mul_f32 v[126:127], v[126:127], v[134:135]
	v_add_f32_e32 v125, 1.0, v125
	v_pk_mul_f32 v[118:119], v[118:119], v[126:127]
	v_mul_f32_e32 v126, 0xbfb8aa3b, v122
	v_mul_f32_e32 v127, 0xbfb8aa3b, v123
	v_exp_f32_e32 v126, v126
	v_exp_f32_e32 v127, v127
	v_rcp_f32_e32 v125, v125
	v_add_f32_e32 v126, 1.0, v126
	v_add_f32_e32 v127, 1.0, v127
	v_rcp_f32_e32 v126, v126
	v_rcp_f32_e32 v127, v127
	v_pk_mul_f32 v[120:121], v[120:121], v[124:125]
	v_pk_mul_f32 v[122:123], v[122:123], v[126:127]
	s_nop 0
	v_pk_mul_f32 v[122:123], v[114:115], v[122:123]
	v_pk_mul_f32 v[114:115], v[112:113], v[120:121]
	v_cvt_pk_bf16_f32 v112, v116, v117
	v_mad_i64_i32 v[116:117], s[12:13], v130, s49, v[128:129]
	v_lshl_add_u64 v[116:117], v[116:117], 0, s[10:11]
	v_lshl_add_u64 v[116:117], v[116:117], 0, s[0:1]
	v_cvt_pk_bf16_f32 v113, v118, v119
	v_cvt_pk_bf16_f32 v114, v114, v115
	v_cvt_pk_bf16_f32 v115, v122, v123
	v_lshl_add_u64 v[116:117], v[116:117], 0, v[152:153]
	global_store_dwordx4 v[116:117], v[112:115], off
	s_nop 1
	v_or_b32_e32 v112, 32, v162
	v_ashrrev_i32_e32 v113, 31, v112
	v_lshl_add_u64 v[114:115], v[112:113], 2, s[18:19]
	s_nop 1
	v_fmamk_f32 v113, v179, 0x3a000000, v172
	v_rsq_f32_e32 v114, v113
	s_nop 0
	v_pk_fma_f32 v[108:109], v[108:109], v[114:115], v[44:45] op_sel_hi:[1,0,1]
	s_nop 0
	v_mul_f32_e32 v113, 0xbfb8aa3b, v108
	v_exp_f32_e32 v113, v113
	v_pk_fma_f32 v[110:111], v[110:111], v[114:115], v[46:47] op_sel_hi:[1,0,1]
	v_pk_fma_f32 v[106:107], v[106:107], v[114:115], v[38:39] op_sel_hi:[1,0,1]
	v_pk_fma_f32 v[104:105], v[104:105], v[114:115], v[36:37] op_sel_hi:[1,0,1]
	v_add_f32_e32 v113, 1.0, v113
	v_pk_fma_f32 v[100:101], v[100:101], v[114:115], v[40:41] op_sel_hi:[1,0,1]
	v_pk_fma_f32 v[102:103], v[102:103], v[114:115], v[42:43] op_sel_hi:[1,0,1]
	v_pk_fma_f32 v[96:97], v[96:97], v[114:115], v[32:33] op_sel_hi:[1,0,1]
	v_pk_fma_f32 v[98:99], v[98:99], v[114:115], v[34:35] op_sel_hi:[1,0,1]
	v_rcp_f32_e32 v114, v113
	v_mul_f32_e32 v113, 0xbfb8aa3b, v109
	v_exp_f32_e32 v113, v113
	s_nop 0
	v_add_f32_e32 v113, 1.0, v113
	v_rcp_f32_e32 v115, v113
	v_mul_f32_e32 v113, 0xbfb8aa3b, v110
	v_exp_f32_e32 v113, v113
	v_pk_mul_f32 v[108:109], v[108:109], v[114:115]
	s_nop 0
	v_pk_mul_f32 v[100:101], v[100:101], v[108:109]
	v_add_f32_e32 v113, 1.0, v113
	v_rcp_f32_e32 v116, v113
	v_mul_f32_e32 v113, 0xbfb8aa3b, v111
	v_exp_f32_e32 v113, v113
	v_mul_f32_e32 v108, 0xbfb8aa3b, v104
	v_mul_f32_e32 v109, 0xbfb8aa3b, v105
	v_exp_f32_e32 v108, v108
	v_add_f32_e32 v113, 1.0, v113
	v_rcp_f32_e32 v117, v113
	v_exp_f32_e32 v109, v109
	v_add_f32_e32 v108, 1.0, v108
	v_rcp_f32_e32 v108, v108
	v_pk_mul_f32 v[110:111], v[110:111], v[116:117]
	v_add_f32_e32 v109, 1.0, v109
	v_pk_mul_f32 v[102:103], v[102:103], v[110:111]
	v_mul_f32_e32 v110, 0xbfb8aa3b, v106
	v_mul_f32_e32 v111, 0xbfb8aa3b, v107
	v_exp_f32_e32 v110, v110
	v_exp_f32_e32 v111, v111
	v_rcp_f32_e32 v109, v109
	v_add_f32_e32 v110, 1.0, v110
	v_add_f32_e32 v111, 1.0, v111
	v_rcp_f32_e32 v110, v110
	v_rcp_f32_e32 v111, v111
	v_pk_mul_f32 v[104:105], v[104:105], v[108:109]
	v_pk_mul_f32 v[106:107], v[106:107], v[110:111]
	s_nop 0
	v_pk_mul_f32 v[106:107], v[98:99], v[106:107]
	v_pk_mul_f32 v[98:99], v[96:97], v[104:105]
	v_cvt_pk_bf16_f32 v96, v100, v101
	v_mad_i64_i32 v[100:101], s[12:13], v112, s49, v[128:129]
	v_lshl_add_u64 v[100:101], v[100:101], 0, s[10:11]
	v_lshl_add_u64 v[100:101], v[100:101], 0, s[0:1]
	v_cvt_pk_bf16_f32 v97, v102, v103
	v_cvt_pk_bf16_f32 v98, v98, v99
	v_cvt_pk_bf16_f32 v99, v106, v107
	v_lshl_add_u64 v[100:101], v[100:101], 0, v[152:153]
	global_store_dwordx4 v[100:101], v[96:99], off
	s_nop 1
	v_or_b32_e32 v96, 48, v162
	v_ashrrev_i32_e32 v97, 31, v96
	v_lshl_add_u64 v[98:99], v[96:97], 2, s[18:19]
	s_nop 1
	v_fmamk_f32 v97, v180, 0x3a000000, v172
	v_rsq_f32_e32 v98, v97
	s_nop 0
	v_pk_fma_f32 v[92:93], v[92:93], v[98:99], v[44:45] op_sel_hi:[1,0,1]
	s_nop 0
	v_mul_f32_e32 v97, 0xbfb8aa3b, v92
	v_exp_f32_e32 v97, v97
	v_pk_fma_f32 v[94:95], v[94:95], v[98:99], v[46:47] op_sel_hi:[1,0,1]
	v_pk_fma_f32 v[90:91], v[90:91], v[98:99], v[38:39] op_sel_hi:[1,0,1]
	v_pk_fma_f32 v[88:89], v[88:89], v[98:99], v[36:37] op_sel_hi:[1,0,1]
	v_add_f32_e32 v97, 1.0, v97
	v_pk_fma_f32 v[84:85], v[84:85], v[98:99], v[40:41] op_sel_hi:[1,0,1]
	v_pk_fma_f32 v[86:87], v[86:87], v[98:99], v[42:43] op_sel_hi:[1,0,1]
	v_pk_fma_f32 v[80:81], v[80:81], v[98:99], v[32:33] op_sel_hi:[1,0,1]
	v_pk_fma_f32 v[82:83], v[82:83], v[98:99], v[34:35] op_sel_hi:[1,0,1]
	v_rcp_f32_e32 v98, v97
	v_mul_f32_e32 v97, 0xbfb8aa3b, v93
	v_exp_f32_e32 v97, v97
	s_nop 0
	v_add_f32_e32 v97, 1.0, v97
	v_rcp_f32_e32 v99, v97
	v_mul_f32_e32 v97, 0xbfb8aa3b, v94
	v_exp_f32_e32 v97, v97
	v_pk_mul_f32 v[92:93], v[92:93], v[98:99]
	s_nop 0
	v_pk_mul_f32 v[84:85], v[84:85], v[92:93]
	v_add_f32_e32 v97, 1.0, v97
	v_rcp_f32_e32 v100, v97
	v_mul_f32_e32 v97, 0xbfb8aa3b, v95
	v_exp_f32_e32 v97, v97
	v_mul_f32_e32 v92, 0xbfb8aa3b, v88
	v_mul_f32_e32 v93, 0xbfb8aa3b, v89
	v_exp_f32_e32 v92, v92
	v_add_f32_e32 v97, 1.0, v97
	v_rcp_f32_e32 v101, v97
	v_exp_f32_e32 v93, v93
	v_add_f32_e32 v92, 1.0, v92
	v_rcp_f32_e32 v92, v92
	v_pk_mul_f32 v[94:95], v[94:95], v[100:101]
	v_add_f32_e32 v93, 1.0, v93
	v_pk_mul_f32 v[86:87], v[86:87], v[94:95]
	v_mul_f32_e32 v94, 0xbfb8aa3b, v90
	v_mul_f32_e32 v95, 0xbfb8aa3b, v91
	v_exp_f32_e32 v94, v94
	v_exp_f32_e32 v95, v95
	v_rcp_f32_e32 v93, v93
	v_add_f32_e32 v94, 1.0, v94
	v_add_f32_e32 v95, 1.0, v95
	v_rcp_f32_e32 v94, v94
	v_rcp_f32_e32 v95, v95
	v_pk_mul_f32 v[88:89], v[88:89], v[92:93]
	v_pk_mul_f32 v[90:91], v[90:91], v[94:95]
	s_nop 0
	v_pk_mul_f32 v[90:91], v[82:83], v[90:91]
	v_pk_mul_f32 v[82:83], v[80:81], v[88:89]
	v_cvt_pk_bf16_f32 v80, v84, v85
	v_mad_i64_i32 v[84:85], s[12:13], v96, s49, v[128:129]
	v_lshl_add_u64 v[84:85], v[84:85], 0, s[10:11]
	v_lshl_add_u64 v[84:85], v[84:85], 0, s[0:1]
	v_cvt_pk_bf16_f32 v81, v86, v87
	v_cvt_pk_bf16_f32 v82, v82, v83
	v_cvt_pk_bf16_f32 v83, v90, v91
	v_lshl_add_u64 v[84:85], v[84:85], 0, v[152:153]
	global_store_dwordx4 v[84:85], v[80:83], off
	s_nop 1
	v_add_u32_e32 v84, 0x80, v162
	v_fmamk_f32 v80, v181, 0x3a000000, v172
	v_rsq_f32_e32 v80, v80
	s_nop 0
	v_pk_fma_f32 v[78:79], v[78:79], v[80:81], v[46:47] op_sel_hi:[1,0,1]
	v_pk_fma_f32 v[76:77], v[76:77], v[80:81], v[44:45] op_sel_hi:[1,0,1]
	v_pk_fma_f32 v[74:75], v[74:75], v[80:81], v[38:39] op_sel_hi:[1,0,1]
	v_pk_fma_f32 v[72:73], v[72:73], v[80:81], v[36:37] op_sel_hi:[1,0,1]
	v_pk_fma_f32 v[68:69], v[68:69], v[80:81], v[40:41] op_sel_hi:[1,0,1]
	v_pk_fma_f32 v[70:71], v[70:71], v[80:81], v[42:43] op_sel_hi:[1,0,1]
	v_pk_fma_f32 v[64:65], v[64:65], v[80:81], v[32:33] op_sel_hi:[1,0,1]
	v_pk_fma_f32 v[66:67], v[66:67], v[80:81], v[34:35] op_sel_hi:[1,0,1]
	v_mul_f32_e32 v80, 0xbfb8aa3b, v76
	v_mul_f32_e32 v81, 0xbfb8aa3b, v77
	v_mul_f32_e32 v82, 0xbfb8aa3b, v78
	v_mul_f32_e32 v83, 0xbfb8aa3b, v79
	v_exp_f32_e32 v80, v80
	v_exp_f32_e32 v81, v81
	v_exp_f32_e32 v82, v82
	v_exp_f32_e32 v83, v83
	v_add_f32_e32 v80, 1.0, v80
	v_add_f32_e32 v81, 1.0, v81
	v_add_f32_e32 v82, 1.0, v82
	v_add_f32_e32 v83, 1.0, v83
	v_rcp_f32_e32 v80, v80
	v_rcp_f32_e32 v81, v81
	v_rcp_f32_e32 v82, v82
	v_rcp_f32_e32 v83, v83
	v_pk_mul_f32 v[76:77], v[76:77], v[80:81]
	s_nop 0
	v_pk_mul_f32 v[68:69], v[68:69], v[76:77]
	v_pk_mul_f32 v[78:79], v[78:79], v[82:83]
	v_mul_f32_e32 v76, 0xbfb8aa3b, v72
	v_pk_mul_f32 v[70:71], v[70:71], v[78:79]
	v_mul_f32_e32 v77, 0xbfb8aa3b, v73
	v_mul_f32_e32 v78, 0xbfb8aa3b, v74
	v_mul_f32_e32 v79, 0xbfb8aa3b, v75
	v_exp_f32_e32 v76, v76
	v_exp_f32_e32 v77, v77
	v_exp_f32_e32 v78, v78
	v_exp_f32_e32 v79, v79
	v_add_f32_e32 v76, 1.0, v76
	v_add_f32_e32 v77, 1.0, v77
	v_add_f32_e32 v78, 1.0, v78
	v_add_f32_e32 v79, 1.0, v79
	v_rcp_f32_e32 v76, v76
	v_rcp_f32_e32 v77, v77
	v_rcp_f32_e32 v78, v78
	v_rcp_f32_e32 v79, v79
	v_pk_mul_f32 v[72:73], v[72:73], v[76:77]
	v_pk_mul_f32 v[74:75], v[74:75], v[78:79]
	s_nop 0
	v_pk_mul_f32 v[74:75], v[66:67], v[74:75]
	v_pk_mul_f32 v[66:67], v[64:65], v[72:73]
	v_cvt_pk_bf16_f32 v64, v68, v69
	v_mad_i64_i32 v[68:69], s[12:13], v84, s49, v[128:129]
	v_lshl_add_u64 v[68:69], v[68:69], 0, s[10:11]
	v_lshl_add_u64 v[68:69], v[68:69], 0, s[0:1]
	v_cvt_pk_bf16_f32 v65, v70, v71
	v_cvt_pk_bf16_f32 v66, v66, v67
	v_cvt_pk_bf16_f32 v67, v74, v75
	v_lshl_add_u64 v[68:69], v[68:69], 0, v[152:153]
	global_store_dwordx4 v[68:69], v[64:67], off
	s_nop 1
	v_add_u32_e32 v68, 0x90, v162
	v_fmamk_f32 v64, v182, 0x3a000000, v172
	v_rsq_f32_e32 v64, v64
	s_nop 0
	v_pk_fma_f32 v[62:63], v[62:63], v[64:65], v[46:47] op_sel_hi:[1,0,1]
	v_pk_fma_f32 v[60:61], v[60:61], v[64:65], v[44:45] op_sel_hi:[1,0,1]
	v_pk_fma_f32 v[58:59], v[58:59], v[64:65], v[38:39] op_sel_hi:[1,0,1]
	v_pk_fma_f32 v[56:57], v[56:57], v[64:65], v[36:37] op_sel_hi:[1,0,1]
	v_pk_fma_f32 v[52:53], v[52:53], v[64:65], v[40:41] op_sel_hi:[1,0,1]
	v_pk_fma_f32 v[54:55], v[54:55], v[64:65], v[42:43] op_sel_hi:[1,0,1]
	v_pk_fma_f32 v[48:49], v[48:49], v[64:65], v[32:33] op_sel_hi:[1,0,1]
	v_pk_fma_f32 v[50:51], v[50:51], v[64:65], v[34:35] op_sel_hi:[1,0,1]
	v_mul_f32_e32 v64, 0xbfb8aa3b, v60
	v_mul_f32_e32 v65, 0xbfb8aa3b, v61
	v_mul_f32_e32 v66, 0xbfb8aa3b, v62
	v_mul_f32_e32 v67, 0xbfb8aa3b, v63
	v_exp_f32_e32 v64, v64
	v_exp_f32_e32 v65, v65
	v_exp_f32_e32 v66, v66
	v_exp_f32_e32 v67, v67
	v_add_f32_e32 v64, 1.0, v64
	v_add_f32_e32 v65, 1.0, v65
	v_add_f32_e32 v66, 1.0, v66
	v_add_f32_e32 v67, 1.0, v67
	v_rcp_f32_e32 v64, v64
	v_rcp_f32_e32 v65, v65
	v_rcp_f32_e32 v66, v66
	v_rcp_f32_e32 v67, v67
	v_pk_mul_f32 v[60:61], v[60:61], v[64:65]
	s_nop 0
	v_pk_mul_f32 v[52:53], v[52:53], v[60:61]
	v_pk_mul_f32 v[62:63], v[62:63], v[66:67]
	v_mul_f32_e32 v60, 0xbfb8aa3b, v56
	v_pk_mul_f32 v[54:55], v[54:55], v[62:63]
	v_mul_f32_e32 v61, 0xbfb8aa3b, v57
	v_mul_f32_e32 v62, 0xbfb8aa3b, v58
	v_mul_f32_e32 v63, 0xbfb8aa3b, v59
	v_exp_f32_e32 v60, v60
	v_exp_f32_e32 v61, v61
	v_exp_f32_e32 v62, v62
	v_exp_f32_e32 v63, v63
	v_add_f32_e32 v60, 1.0, v60
	v_add_f32_e32 v61, 1.0, v61
	v_add_f32_e32 v62, 1.0, v62
	v_add_f32_e32 v63, 1.0, v63
	v_rcp_f32_e32 v60, v60
	v_rcp_f32_e32 v61, v61
	v_rcp_f32_e32 v62, v62
	v_rcp_f32_e32 v63, v63
	v_pk_mul_f32 v[56:57], v[56:57], v[60:61]
	v_pk_mul_f32 v[58:59], v[58:59], v[62:63]
	s_nop 0
	v_pk_mul_f32 v[58:59], v[50:51], v[58:59]
	v_pk_mul_f32 v[50:51], v[48:49], v[56:57]
	v_cvt_pk_bf16_f32 v48, v52, v53
	v_mad_i64_i32 v[52:53], s[12:13], v68, s49, v[128:129]
	v_lshl_add_u64 v[52:53], v[52:53], 0, s[10:11]
	v_lshl_add_u64 v[52:53], v[52:53], 0, s[0:1]
	v_cvt_pk_bf16_f32 v49, v54, v55
	v_cvt_pk_bf16_f32 v50, v50, v51
	v_cvt_pk_bf16_f32 v51, v58, v59
	v_lshl_add_u64 v[52:53], v[52:53], 0, v[152:153]
	global_store_dwordx4 v[52:53], v[48:51], off
	s_nop 1
	v_add_u32_e32 v52, 0xa0, v162
	v_fmamk_f32 v48, v183, 0x3a000000, v172
	v_rsq_f32_e32 v48, v48
	s_nop 0
	v_pk_fma_f32 v[30:31], v[30:31], v[48:49], v[46:47] op_sel_hi:[1,0,1]
	v_pk_fma_f32 v[28:29], v[28:29], v[48:49], v[44:45] op_sel_hi:[1,0,1]
	v_pk_fma_f32 v[26:27], v[26:27], v[48:49], v[38:39] op_sel_hi:[1,0,1]
	v_pk_fma_f32 v[24:25], v[24:25], v[48:49], v[36:37] op_sel_hi:[1,0,1]
	v_pk_fma_f32 v[20:21], v[20:21], v[48:49], v[40:41] op_sel_hi:[1,0,1]
	v_pk_fma_f32 v[22:23], v[22:23], v[48:49], v[42:43] op_sel_hi:[1,0,1]
	v_pk_fma_f32 v[16:17], v[16:17], v[48:49], v[32:33] op_sel_hi:[1,0,1]
	v_pk_fma_f32 v[18:19], v[18:19], v[48:49], v[34:35] op_sel_hi:[1,0,1]
	v_mul_f32_e32 v48, 0xbfb8aa3b, v28
	v_mul_f32_e32 v49, 0xbfb8aa3b, v29
	v_mul_f32_e32 v50, 0xbfb8aa3b, v30
	v_mul_f32_e32 v51, 0xbfb8aa3b, v31
	v_exp_f32_e32 v48, v48
	v_exp_f32_e32 v49, v49
	v_exp_f32_e32 v50, v50
	v_exp_f32_e32 v51, v51
	v_add_f32_e32 v48, 1.0, v48
	v_add_f32_e32 v49, 1.0, v49
	v_add_f32_e32 v50, 1.0, v50
	v_add_f32_e32 v51, 1.0, v51
	v_rcp_f32_e32 v48, v48
	v_rcp_f32_e32 v49, v49
	v_rcp_f32_e32 v50, v50
	v_rcp_f32_e32 v51, v51
	v_pk_mul_f32 v[28:29], v[28:29], v[48:49]
	s_nop 0
	v_pk_mul_f32 v[20:21], v[20:21], v[28:29]
	v_pk_mul_f32 v[30:31], v[30:31], v[50:51]
	v_mul_f32_e32 v28, 0xbfb8aa3b, v24
	v_pk_mul_f32 v[22:23], v[22:23], v[30:31]
	v_mul_f32_e32 v29, 0xbfb8aa3b, v25
	v_mul_f32_e32 v30, 0xbfb8aa3b, v26
	v_mul_f32_e32 v31, 0xbfb8aa3b, v27
	v_exp_f32_e32 v28, v28
	v_exp_f32_e32 v29, v29
	v_exp_f32_e32 v30, v30
	v_exp_f32_e32 v31, v31
	v_add_f32_e32 v28, 1.0, v28
	v_add_f32_e32 v29, 1.0, v29
	v_add_f32_e32 v30, 1.0, v30
	v_add_f32_e32 v31, 1.0, v31
	v_rcp_f32_e32 v28, v28
	v_rcp_f32_e32 v29, v29
	v_rcp_f32_e32 v30, v30
	v_rcp_f32_e32 v31, v31
	v_pk_mul_f32 v[24:25], v[24:25], v[28:29]
	v_pk_mul_f32 v[26:27], v[26:27], v[30:31]
	s_nop 0
	v_pk_mul_f32 v[26:27], v[18:19], v[26:27]
	v_pk_mul_f32 v[18:19], v[16:17], v[24:25]
	v_cvt_pk_bf16_f32 v16, v20, v21
	v_mad_i64_i32 v[20:21], s[12:13], v52, s49, v[128:129]
	v_lshl_add_u64 v[20:21], v[20:21], 0, s[10:11]
	v_lshl_add_u64 v[20:21], v[20:21], 0, s[0:1]
	v_cvt_pk_bf16_f32 v17, v22, v23
	v_cvt_pk_bf16_f32 v18, v18, v19
	v_cvt_pk_bf16_f32 v19, v26, v27
	v_lshl_add_u64 v[20:21], v[20:21], 0, v[152:153]
	global_store_dwordx4 v[20:21], v[16:19], off
	s_nop 1
	v_add_u32_e32 v20, 0xb0, v162
	v_fmamk_f32 v16, v184, 0x3a000000, v172
	v_rsq_f32_e32 v16, v16
	s_nop 0
	v_pk_fma_f32 v[14:15], v[14:15], v[16:17], v[46:47] op_sel_hi:[1,0,1]
	v_pk_fma_f32 v[12:13], v[12:13], v[16:17], v[44:45] op_sel_hi:[1,0,1]
	v_pk_fma_f32 v[10:11], v[10:11], v[16:17], v[38:39] op_sel_hi:[1,0,1]
	v_pk_fma_f32 v[8:9], v[8:9], v[16:17], v[36:37] op_sel_hi:[1,0,1]
	v_pk_fma_f32 v[4:5], v[4:5], v[16:17], v[40:41] op_sel_hi:[1,0,1]
	v_pk_fma_f32 v[6:7], v[6:7], v[16:17], v[42:43] op_sel_hi:[1,0,1]
	v_pk_fma_f32 v[0:1], v[0:1], v[16:17], v[32:33] op_sel_hi:[1,0,1]
	v_pk_fma_f32 v[2:3], v[2:3], v[16:17], v[34:35] op_sel_hi:[1,0,1]
	v_mul_f32_e32 v16, 0xbfb8aa3b, v12
	v_mul_f32_e32 v17, 0xbfb8aa3b, v13
	v_mul_f32_e32 v18, 0xbfb8aa3b, v14
	v_mul_f32_e32 v19, 0xbfb8aa3b, v15
	v_exp_f32_e32 v16, v16
	v_exp_f32_e32 v17, v17
	v_exp_f32_e32 v18, v18
	v_exp_f32_e32 v19, v19
	v_add_f32_e32 v16, 1.0, v16
	v_add_f32_e32 v17, 1.0, v17
	v_add_f32_e32 v18, 1.0, v18
	v_add_f32_e32 v19, 1.0, v19
	v_rcp_f32_e32 v16, v16
	v_rcp_f32_e32 v17, v17
	v_rcp_f32_e32 v18, v18
	v_rcp_f32_e32 v19, v19
	v_pk_mul_f32 v[12:13], v[12:13], v[16:17]
	s_nop 0
	v_pk_mul_f32 v[4:5], v[4:5], v[12:13]
	v_pk_mul_f32 v[14:15], v[14:15], v[18:19]
	v_mul_f32_e32 v12, 0xbfb8aa3b, v8
	v_pk_mul_f32 v[6:7], v[6:7], v[14:15]
	v_mul_f32_e32 v13, 0xbfb8aa3b, v9
	v_mul_f32_e32 v14, 0xbfb8aa3b, v10
	v_mul_f32_e32 v15, 0xbfb8aa3b, v11
	v_exp_f32_e32 v12, v12
	v_exp_f32_e32 v13, v13
	v_exp_f32_e32 v14, v14
	v_exp_f32_e32 v15, v15
	v_add_f32_e32 v12, 1.0, v12
	v_add_f32_e32 v13, 1.0, v13
	v_add_f32_e32 v14, 1.0, v14
	v_add_f32_e32 v15, 1.0, v15
	v_rcp_f32_e32 v12, v12
	v_rcp_f32_e32 v13, v13
	v_rcp_f32_e32 v14, v14
	v_rcp_f32_e32 v15, v15
	v_pk_mul_f32 v[8:9], v[8:9], v[12:13]
	v_pk_mul_f32 v[10:11], v[10:11], v[14:15]
	s_nop 0
	v_pk_mul_f32 v[10:11], v[2:3], v[10:11]
	v_pk_mul_f32 v[2:3], v[0:1], v[8:9]
	v_cvt_pk_bf16_f32 v0, v4, v5
	v_mad_i64_i32 v[4:5], s[12:13], v20, s49, v[128:129]
	v_lshl_add_u64 v[4:5], v[4:5], 0, s[10:11]
	v_lshl_add_u64 v[4:5], v[4:5], 0, s[0:1]
	v_cvt_pk_bf16_f32 v1, v6, v7
	v_cvt_pk_bf16_f32 v2, v2, v3
	v_cvt_pk_bf16_f32 v3, v10, v11
	v_lshl_add_u64 v[4:5], v[4:5], 0, v[152:153]
	s_mov_b64 s[10:11], -1
	global_store_dwordx4 v[4:5], v[0:3], off
	s_cbranch_vccnz .LBB0_842
	s_andn2_b64 vcc, exec, s[4:5]
	s_cbranch_vccnz .LBB0_841
	s_barrier
	s_branch .LBB0_841
